# cache policy: gate/up (SwiGLU) epilogue act stores non-temporal
# baseline (speedup 1.0000x reference)
.LBB0_107:
	v_mul_f32_e32 v150, 0xbfb8aa3b, v124
	v_exp_f32_e32 v150, v150
	v_mul_f32_e32 v151, 0xbfb8aa3b, v125
	v_exp_f32_e32 v151, v151
	v_mul_f32_e32 v155, 0xbfb8aa3b, v126
	v_add_f32_e32 v150, 1.0, v150
	v_rcp_f32_e32 v158, v150
	v_add_f32_e32 v150, 1.0, v151
	v_rcp_f32_e32 v159, v150
	v_exp_f32_e32 v155, v155
	v_lshl_or_b32 v156, s52, 7, v152
	v_lshl_add_u32 v154, s53, 8, v135
	v_pk_mul_f32 v[124:125], v[124:125], v[158:159]
	v_mul_f32_e32 v158, 0xbfb8aa3b, v127
	v_exp_f32_e32 v158, v158
	v_pk_mul_f32 v[120:121], v[120:121], v[124:125]
	v_add_f32_e32 v124, 1.0, v155
	v_mul_f32_e32 v155, 0xbfb8aa3b, v116
	v_add_f32_e32 v125, 1.0, v158
	v_rcp_f32_e32 v124, v124
	v_rcp_f32_e32 v125, v125
	v_exp_f32_e32 v155, v155
	v_mul_f32_e32 v158, 0xbfb8aa3b, v117
	v_exp_f32_e32 v158, v158
	v_pk_mul_f32 v[124:125], v[126:127], v[124:125]
	v_add_f32_e32 v126, 1.0, v155
	v_mul_f32_e32 v155, 0xbfb8aa3b, v118
	v_add_f32_e32 v127, 1.0, v158
	v_exp_f32_e32 v155, v155
	v_mul_f32_e32 v158, 0xbfb8aa3b, v119
	v_exp_f32_e32 v159, v158
	v_rcp_f32_e32 v126, v126
	v_add_f32_e32 v155, 1.0, v155
	v_rcp_f32_e32 v127, v127
	v_rcp_f32_e32 v158, v155
	v_add_f32_e32 v155, 1.0, v159
	v_rcp_f32_e32 v159, v155
	v_pk_mul_f32 v[116:117], v[116:117], v[126:127]
	v_ashrrev_i32_e32 v157, 31, v156
	v_pk_mul_f32 v[116:117], v[112:113], v[116:117]
	v_pk_mul_f32 v[112:113], v[118:119], v[158:159]
	v_cvt_pk_bf16_f32 v116, v116, v117
	v_pk_mul_f32 v[118:119], v[114:115], v[112:113]
	v_mov_b64_e32 v[150:151], s[22:23]
	v_cvt_pk_bf16_f32 v117, v118, v119
	v_mul_f32_e32 v118, 0xbfb8aa3b, v108
	v_mul_f32_e32 v119, 0xbfb8aa3b, v109
	v_exp_f32_e32 v118, v118
	v_exp_f32_e32 v119, v119
	s_movk_i32 s26, 0x1600
	v_mad_i64_i32 v[160:161], s[24:25], v154, s26, v[150:151]
	v_pk_mul_f32 v[122:123], v[122:123], v[124:125]
	v_lshlrev_b64 v[112:113], 1, v[156:157]
	v_lshl_add_u64 v[124:125], v[160:161], 0, v[112:113]
	v_cvt_pk_bf16_f32 v114, v120, v121
	v_cvt_pk_bf16_f32 v115, v122, v123
	global_store_dwordx4 v[124:125], v[114:117], off nt
	s_and_b64 vcc, exec, s[40:41]
	s_nop 0
	v_add_f32_e32 v114, 1.0, v118
	v_add_f32_e32 v115, 1.0, v119
	v_rcp_f32_e32 v114, v114
	v_rcp_f32_e32 v115, v115
	v_or_b32_e32 v116, 16, v154
	v_mad_i64_i32 v[116:117], s[24:25], v116, s26, v[150:151]
	v_pk_mul_f32 v[108:109], v[108:109], v[114:115]
	v_mul_f32_e32 v114, 0xbfb8aa3b, v110
	v_mul_f32_e32 v115, 0xbfb8aa3b, v111
	v_exp_f32_e32 v114, v114
	v_exp_f32_e32 v115, v115
	v_pk_mul_f32 v[104:105], v[104:105], v[108:109]
	v_add_f32_e32 v108, 1.0, v114
	v_add_f32_e32 v109, 1.0, v115
	v_mul_f32_e32 v114, 0xbfb8aa3b, v100
	v_mul_f32_e32 v115, 0xbfb8aa3b, v101
	v_rcp_f32_e32 v108, v108
	v_rcp_f32_e32 v109, v109
	v_exp_f32_e32 v114, v114
	v_exp_f32_e32 v115, v115
	v_pk_mul_f32 v[108:109], v[110:111], v[108:109]
	v_add_f32_e32 v110, 1.0, v114
	v_add_f32_e32 v111, 1.0, v115
	v_mul_f32_e32 v114, 0xbfb8aa3b, v102
	v_mul_f32_e32 v115, 0xbfb8aa3b, v103
	v_exp_f32_e32 v114, v114
	v_exp_f32_e32 v115, v115
	v_rcp_f32_e32 v110, v110
	v_rcp_f32_e32 v111, v111
	v_add_f32_e32 v114, 1.0, v114
	v_add_f32_e32 v115, 1.0, v115
	v_rcp_f32_e32 v114, v114
	v_rcp_f32_e32 v115, v115
	v_pk_mul_f32 v[100:101], v[100:101], v[110:111]
	v_pk_mul_f32 v[106:107], v[106:107], v[108:109]
	v_pk_mul_f32 v[100:101], v[96:97], v[100:101]
	v_pk_mul_f32 v[96:97], v[102:103], v[114:115]
	v_lshl_add_u64 v[108:109], v[116:117], 0, v[112:113]
	v_pk_mul_f32 v[102:103], v[98:99], v[96:97]
	v_cvt_pk_bf16_f32 v98, v100, v101
	v_mul_f32_e32 v100, 0xbfb8aa3b, v92
	v_mul_f32_e32 v101, 0xbfb8aa3b, v93
	v_exp_f32_e32 v100, v100
	v_exp_f32_e32 v101, v101
	v_cvt_pk_bf16_f32 v96, v104, v105
	v_cvt_pk_bf16_f32 v97, v106, v107
	v_cvt_pk_bf16_f32 v99, v102, v103
	global_store_dwordx4 v[108:109], v[96:99], off nt
	s_nop 1
	v_add_f32_e32 v96, 1.0, v100
	v_add_f32_e32 v97, 1.0, v101
	v_rcp_f32_e32 v96, v96
	v_rcp_f32_e32 v97, v97
	v_or_b32_e32 v98, 32, v154
	v_mad_i64_i32 v[98:99], s[24:25], v98, s26, v[150:151]
	v_pk_mul_f32 v[92:93], v[92:93], v[96:97]
	v_mul_f32_e32 v96, 0xbfb8aa3b, v94
	v_mul_f32_e32 v97, 0xbfb8aa3b, v95
	v_exp_f32_e32 v96, v96
	v_exp_f32_e32 v97, v97
	v_pk_mul_f32 v[88:89], v[88:89], v[92:93]
	v_add_f32_e32 v92, 1.0, v96
	v_add_f32_e32 v93, 1.0, v97
	v_mul_f32_e32 v96, 0xbfb8aa3b, v84
	v_mul_f32_e32 v97, 0xbfb8aa3b, v85
	v_rcp_f32_e32 v92, v92
	v_rcp_f32_e32 v93, v93
	v_exp_f32_e32 v96, v96
	v_exp_f32_e32 v97, v97
	v_pk_mul_f32 v[92:93], v[94:95], v[92:93]
	v_add_f32_e32 v94, 1.0, v96
	v_add_f32_e32 v95, 1.0, v97
	v_mul_f32_e32 v96, 0xbfb8aa3b, v86
	v_mul_f32_e32 v97, 0xbfb8aa3b, v87
	v_exp_f32_e32 v96, v96
	v_exp_f32_e32 v97, v97
	v_rcp_f32_e32 v94, v94
	v_rcp_f32_e32 v95, v95
	v_add_f32_e32 v96, 1.0, v96
	v_add_f32_e32 v97, 1.0, v97
	v_rcp_f32_e32 v96, v96
	v_rcp_f32_e32 v97, v97
	v_pk_mul_f32 v[84:85], v[84:85], v[94:95]
	v_pk_mul_f32 v[90:91], v[90:91], v[92:93]
	v_pk_mul_f32 v[84:85], v[80:81], v[84:85]
	v_pk_mul_f32 v[80:81], v[86:87], v[96:97]
	v_lshl_add_u64 v[92:93], v[98:99], 0, v[112:113]
	v_pk_mul_f32 v[86:87], v[82:83], v[80:81]
	v_cvt_pk_bf16_f32 v82, v84, v85
	v_mul_f32_e32 v84, 0xbfb8aa3b, v76
	v_mul_f32_e32 v85, 0xbfb8aa3b, v77
	v_exp_f32_e32 v84, v84
	v_exp_f32_e32 v85, v85
	v_cvt_pk_bf16_f32 v80, v88, v89
	v_cvt_pk_bf16_f32 v81, v90, v91
	v_cvt_pk_bf16_f32 v83, v86, v87
	global_store_dwordx4 v[92:93], v[80:83], off nt
	s_nop 1
	v_add_f32_e32 v80, 1.0, v84
	v_add_f32_e32 v81, 1.0, v85
	v_rcp_f32_e32 v80, v80
	v_rcp_f32_e32 v81, v81
	v_or_b32_e32 v82, 48, v154
	v_mad_i64_i32 v[82:83], s[24:25], v82, s26, v[150:151]
	v_pk_mul_f32 v[76:77], v[76:77], v[80:81]
	v_mul_f32_e32 v80, 0xbfb8aa3b, v78
	v_mul_f32_e32 v81, 0xbfb8aa3b, v79
	v_exp_f32_e32 v80, v80
	v_exp_f32_e32 v81, v81
	v_pk_mul_f32 v[72:73], v[72:73], v[76:77]
	v_add_f32_e32 v76, 1.0, v80
	v_add_f32_e32 v77, 1.0, v81
	v_mul_f32_e32 v80, 0xbfb8aa3b, v68
	v_mul_f32_e32 v81, 0xbfb8aa3b, v69
	v_rcp_f32_e32 v76, v76
	v_rcp_f32_e32 v77, v77
	v_exp_f32_e32 v80, v80
	v_exp_f32_e32 v81, v81
	v_pk_mul_f32 v[76:77], v[78:79], v[76:77]
	v_add_f32_e32 v78, 1.0, v80
	v_add_f32_e32 v79, 1.0, v81
	v_mul_f32_e32 v80, 0xbfb8aa3b, v70
	v_mul_f32_e32 v81, 0xbfb8aa3b, v71
	v_exp_f32_e32 v80, v80
	v_exp_f32_e32 v81, v81
	v_rcp_f32_e32 v78, v78
	v_rcp_f32_e32 v79, v79
	v_add_f32_e32 v80, 1.0, v80
	v_add_f32_e32 v81, 1.0, v81
	v_rcp_f32_e32 v80, v80
	v_rcp_f32_e32 v81, v81
	v_pk_mul_f32 v[68:69], v[68:69], v[78:79]
	v_pk_mul_f32 v[74:75], v[74:75], v[76:77]
	v_pk_mul_f32 v[68:69], v[64:65], v[68:69]
	v_pk_mul_f32 v[64:65], v[70:71], v[80:81]
	v_lshl_add_u64 v[76:77], v[82:83], 0, v[112:113]
	v_pk_mul_f32 v[70:71], v[66:67], v[64:65]
	v_cvt_pk_bf16_f32 v66, v68, v69
	v_mul_f32_e32 v68, 0xbfb8aa3b, v60
	v_mul_f32_e32 v69, 0xbfb8aa3b, v61
	v_exp_f32_e32 v68, v68
	v_exp_f32_e32 v69, v69
	v_cvt_pk_bf16_f32 v64, v72, v73
	v_cvt_pk_bf16_f32 v65, v74, v75
	v_cvt_pk_bf16_f32 v67, v70, v71
	global_store_dwordx4 v[76:77], v[64:67], off nt
	s_nop 1
	v_add_f32_e32 v64, 1.0, v68
	v_add_f32_e32 v65, 1.0, v69
	v_rcp_f32_e32 v64, v64
	v_rcp_f32_e32 v65, v65
	v_add_u32_e32 v66, 0x80, v154
	v_mad_i64_i32 v[66:67], s[24:25], v66, s26, v[150:151]
	v_pk_mul_f32 v[60:61], v[60:61], v[64:65]
	v_mul_f32_e32 v64, 0xbfb8aa3b, v62
	v_mul_f32_e32 v65, 0xbfb8aa3b, v63
	v_exp_f32_e32 v64, v64
	v_exp_f32_e32 v65, v65
	v_pk_mul_f32 v[56:57], v[56:57], v[60:61]
	v_add_f32_e32 v60, 1.0, v64
	v_add_f32_e32 v61, 1.0, v65
	v_mul_f32_e32 v64, 0xbfb8aa3b, v52
	v_mul_f32_e32 v65, 0xbfb8aa3b, v53
	v_rcp_f32_e32 v60, v60
	v_rcp_f32_e32 v61, v61
	v_exp_f32_e32 v64, v64
	v_exp_f32_e32 v65, v65
	v_pk_mul_f32 v[60:61], v[62:63], v[60:61]
	v_add_f32_e32 v62, 1.0, v64
	v_add_f32_e32 v63, 1.0, v65
	v_mul_f32_e32 v64, 0xbfb8aa3b, v54
	v_mul_f32_e32 v65, 0xbfb8aa3b, v55
	v_exp_f32_e32 v64, v64
	v_exp_f32_e32 v65, v65
	v_rcp_f32_e32 v62, v62
	v_rcp_f32_e32 v63, v63
	v_add_f32_e32 v64, 1.0, v64
	v_add_f32_e32 v65, 1.0, v65
	v_rcp_f32_e32 v64, v64
	v_rcp_f32_e32 v65, v65
	v_pk_mul_f32 v[52:53], v[52:53], v[62:63]
	v_pk_mul_f32 v[58:59], v[58:59], v[60:61]
	v_pk_mul_f32 v[52:53], v[48:49], v[52:53]
	v_pk_mul_f32 v[48:49], v[54:55], v[64:65]
	v_lshl_add_u64 v[60:61], v[66:67], 0, v[112:113]
	v_pk_mul_f32 v[54:55], v[50:51], v[48:49]
	v_cvt_pk_bf16_f32 v50, v52, v53
	v_mul_f32_e32 v52, 0xbfb8aa3b, v44
	v_mul_f32_e32 v53, 0xbfb8aa3b, v45
	v_exp_f32_e32 v52, v52
	v_exp_f32_e32 v53, v53
	v_cvt_pk_bf16_f32 v48, v56, v57
	v_cvt_pk_bf16_f32 v49, v58, v59
	v_cvt_pk_bf16_f32 v51, v54, v55
	global_store_dwordx4 v[60:61], v[48:51], off nt
	s_nop 1
	v_add_f32_e32 v48, 1.0, v52
	v_add_f32_e32 v49, 1.0, v53
	v_rcp_f32_e32 v48, v48
	v_rcp_f32_e32 v49, v49
	v_add_u32_e32 v50, 0x90, v154
	v_mad_i64_i32 v[50:51], s[24:25], v50, s26, v[150:151]
	v_pk_mul_f32 v[44:45], v[44:45], v[48:49]
	v_mul_f32_e32 v48, 0xbfb8aa3b, v46
	v_mul_f32_e32 v49, 0xbfb8aa3b, v47
	v_exp_f32_e32 v48, v48
	v_exp_f32_e32 v49, v49
	v_pk_mul_f32 v[40:41], v[40:41], v[44:45]
	v_add_f32_e32 v44, 1.0, v48
	v_add_f32_e32 v45, 1.0, v49
	v_mul_f32_e32 v48, 0xbfb8aa3b, v36
	v_mul_f32_e32 v49, 0xbfb8aa3b, v37
	v_rcp_f32_e32 v44, v44
	v_rcp_f32_e32 v45, v45
	v_exp_f32_e32 v48, v48
	v_exp_f32_e32 v49, v49
	v_pk_mul_f32 v[44:45], v[46:47], v[44:45]
	v_add_f32_e32 v46, 1.0, v48
	v_add_f32_e32 v47, 1.0, v49
	v_mul_f32_e32 v48, 0xbfb8aa3b, v38
	v_mul_f32_e32 v49, 0xbfb8aa3b, v39
	v_exp_f32_e32 v48, v48
	v_exp_f32_e32 v49, v49
	v_rcp_f32_e32 v46, v46
	v_rcp_f32_e32 v47, v47
	v_add_f32_e32 v48, 1.0, v48
	v_add_f32_e32 v49, 1.0, v49
	v_rcp_f32_e32 v48, v48
	v_rcp_f32_e32 v49, v49
	v_pk_mul_f32 v[36:37], v[36:37], v[46:47]
	v_pk_mul_f32 v[42:43], v[42:43], v[44:45]
	v_pk_mul_f32 v[36:37], v[32:33], v[36:37]
	v_pk_mul_f32 v[32:33], v[38:39], v[48:49]
	v_lshl_add_u64 v[44:45], v[50:51], 0, v[112:113]
	v_pk_mul_f32 v[38:39], v[34:35], v[32:33]
	v_cvt_pk_bf16_f32 v34, v36, v37
	v_mul_f32_e32 v36, 0xbfb8aa3b, v28
	v_mul_f32_e32 v37, 0xbfb8aa3b, v29
	v_exp_f32_e32 v36, v36
	v_exp_f32_e32 v37, v37
	v_cvt_pk_bf16_f32 v32, v40, v41
	v_cvt_pk_bf16_f32 v33, v42, v43
	v_cvt_pk_bf16_f32 v35, v38, v39
	global_store_dwordx4 v[44:45], v[32:35], off nt
	s_nop 1
	v_add_f32_e32 v32, 1.0, v36
	v_add_f32_e32 v33, 1.0, v37
	v_rcp_f32_e32 v32, v32
	v_rcp_f32_e32 v33, v33
	v_add_u32_e32 v34, 0xa0, v154
	v_mad_i64_i32 v[34:35], s[24:25], v34, s26, v[150:151]
	v_pk_mul_f32 v[28:29], v[28:29], v[32:33]
	v_mul_f32_e32 v32, 0xbfb8aa3b, v30
	v_mul_f32_e32 v33, 0xbfb8aa3b, v31
	v_exp_f32_e32 v32, v32
	v_exp_f32_e32 v33, v33
	v_pk_mul_f32 v[24:25], v[24:25], v[28:29]
	v_add_f32_e32 v28, 1.0, v32
	v_add_f32_e32 v29, 1.0, v33
	v_mul_f32_e32 v32, 0xbfb8aa3b, v20
	v_mul_f32_e32 v33, 0xbfb8aa3b, v21
	v_rcp_f32_e32 v28, v28
	v_rcp_f32_e32 v29, v29
	v_exp_f32_e32 v32, v32
	v_exp_f32_e32 v33, v33
	v_pk_mul_f32 v[28:29], v[30:31], v[28:29]
	v_add_f32_e32 v30, 1.0, v32
	v_add_f32_e32 v31, 1.0, v33
	v_mul_f32_e32 v32, 0xbfb8aa3b, v22
	v_mul_f32_e32 v33, 0xbfb8aa3b, v23
	v_exp_f32_e32 v32, v32
	v_exp_f32_e32 v33, v33
	v_rcp_f32_e32 v30, v30
	v_rcp_f32_e32 v31, v31
	v_add_f32_e32 v32, 1.0, v32
	v_add_f32_e32 v33, 1.0, v33
	v_rcp_f32_e32 v32, v32
	v_rcp_f32_e32 v33, v33
	v_pk_mul_f32 v[20:21], v[20:21], v[30:31]
	v_pk_mul_f32 v[26:27], v[26:27], v[28:29]
	v_pk_mul_f32 v[20:21], v[16:17], v[20:21]
	v_pk_mul_f32 v[16:17], v[22:23], v[32:33]
	v_lshl_add_u64 v[28:29], v[34:35], 0, v[112:113]
	v_pk_mul_f32 v[22:23], v[18:19], v[16:17]
	v_cvt_pk_bf16_f32 v18, v20, v21
	v_mul_f32_e32 v20, 0xbfb8aa3b, v12
	v_mul_f32_e32 v21, 0xbfb8aa3b, v13
	v_exp_f32_e32 v20, v20
	v_exp_f32_e32 v21, v21
	v_cvt_pk_bf16_f32 v16, v24, v25
	v_cvt_pk_bf16_f32 v17, v26, v27
	v_cvt_pk_bf16_f32 v19, v22, v23
	global_store_dwordx4 v[28:29], v[16:19], off nt
	s_nop 1
	v_add_f32_e32 v16, 1.0, v20
	v_add_f32_e32 v17, 1.0, v21
	v_rcp_f32_e32 v16, v16
	v_rcp_f32_e32 v17, v17
	v_add_u32_e32 v18, 0xb0, v154
	v_mad_i64_i32 v[18:19], s[24:25], v18, s26, v[150:151]
	v_pk_mul_f32 v[12:13], v[12:13], v[16:17]
	v_mul_f32_e32 v16, 0xbfb8aa3b, v14
	v_mul_f32_e32 v17, 0xbfb8aa3b, v15
	v_exp_f32_e32 v16, v16
	v_exp_f32_e32 v17, v17
	v_pk_mul_f32 v[8:9], v[8:9], v[12:13]
	s_mov_b64 s[24:25], -1
	v_add_f32_e32 v12, 1.0, v16
	v_add_f32_e32 v13, 1.0, v17
	v_mul_f32_e32 v16, 0xbfb8aa3b, v4
	v_mul_f32_e32 v17, 0xbfb8aa3b, v5
	v_rcp_f32_e32 v12, v12
	v_rcp_f32_e32 v13, v13
	v_exp_f32_e32 v16, v16
	v_exp_f32_e32 v17, v17
	v_pk_mul_f32 v[12:13], v[14:15], v[12:13]
	v_add_f32_e32 v14, 1.0, v16
	v_add_f32_e32 v15, 1.0, v17
	v_mul_f32_e32 v16, 0xbfb8aa3b, v6
	v_mul_f32_e32 v17, 0xbfb8aa3b, v7
	v_exp_f32_e32 v16, v16
	v_exp_f32_e32 v17, v17
	v_rcp_f32_e32 v14, v14
	v_rcp_f32_e32 v15, v15
	v_add_f32_e32 v16, 1.0, v16
	v_add_f32_e32 v17, 1.0, v17
	v_rcp_f32_e32 v16, v16
	v_rcp_f32_e32 v17, v17
	v_pk_mul_f32 v[4:5], v[4:5], v[14:15]
	v_pk_mul_f32 v[10:11], v[10:11], v[12:13]
	v_pk_mul_f32 v[4:5], v[0:1], v[4:5]
	v_pk_mul_f32 v[0:1], v[6:7], v[16:17]
	v_lshl_add_u64 v[12:13], v[18:19], 0, v[112:113]
	v_pk_mul_f32 v[6:7], v[2:3], v[0:1]
	v_cvt_pk_bf16_f32 v0, v8, v9
	v_cvt_pk_bf16_f32 v1, v10, v11
	v_cvt_pk_bf16_f32 v2, v4, v5
	v_cvt_pk_bf16_f32 v3, v6, v7
	global_store_dwordx4 v[12:13], v[0:3], off nt
	s_cbranch_vccnz .LBB0_94
	s_andn2_b64 vcc, exec, s[12:13]
	s_cbranch_vccnz .LBB0_93
	s_barrier
	s_branch .LBB0_93
